# rows_ln and rows_ple rows remapped so each XCD normalises the same 4096 rows its f1/f3 tiles write (L2 locality)
# baseline (speedup 1.0000x reference)
; DI int tidx() { int t = threadIdx.x & 255; asm volatile("" : "+v"(t)); return t; }
; DI int vbid() { return (int)blockIdx.x * 2 + half_(); }
; DI int vgrid() { return (int)gridDim.x * 2; }
; DI void rows_ln(PREF p, int l) {
;   const int tid = tidx(), lane = tid & 63, w = tid >> 6;
;   float gg[16], bb[16];
; #pragma unroll
;   for (int h = 0; h < 2; ++h) {
;     const int c = h * 512 + lane * 8;
;     const float4 g0 = *(const float4*)(p.ln_g + l * 1024 + c), g1 = *(const float4*)(p.ln_g + l * 1024 + c + 4);
;     const float4 b0 = *(const float4*)(p.ln_b + l * 1024 + c), b1 = *(const float4*)(p.ln_b + l * 1024 + c + 4);
;     gg[h * 8 + 0] = g0.x; gg[h * 8 + 1] = g0.y; gg[h * 8 + 2] = g0.z; gg[h * 8 + 3] = g0.w;
;     gg[h * 8 + 4] = g1.x; gg[h * 8 + 5] = g1.y; gg[h * 8 + 6] = g1.z; gg[h * 8 + 7] = g1.w;
;     bb[h * 8 + 0] = b0.x; bb[h * 8 + 1] = b0.y; bb[h * 8 + 2] = b0.z; bb[h * 8 + 3] = b0.w;
;     bb[h * 8 + 4] = b1.x; bb[h * 8 + 5] = b1.y; bb[h * 8 + 6] = b1.z; bb[h * 8 + 7] = b1.w;
;   }
;   for (int row = vbid() * 4 + w; row < T_ / 2; row += vgrid() * 4) {
;     u32x4 raw[2][2];
; #pragma unroll
;     for (int k = 0; k < 2; ++k) {
;       const u16* src = (const u16*)p.fbuf + (size_t)(row + k * (T_ / 2)) * 1024;
;       raw[k][0] = *(const u32x4*)(src + lane * 8);
;       raw[k][1] = *(const u32x4*)(src + 512 + lane * 8);
;     }
.LBB0_52:
	v_writelane_b32 v254, s0, 51
	s_and_b64 vcc, exec, s[12:13]
	s_nop 0
	v_writelane_b32 v254, s1, 52
	s_cbranch_vccz .LBB0_57
	v_readfirstlane_b32 s0, v168
	s_lshr_b32 s0, s0, 6
	v_mov_b32_e32 v0, v169
	s_and_b32 s16, s0, 0x3fffffc
	v_readlane_b32 s0, v254, 0
	s_and_b32 s17, s0, 7
	s_lshl_b32 s17, s17, 12
	s_andn2_b32 s0, s0, 7
	s_add_i32 s0, s0, s17
	s_add_i32 s0, s16, s0
	v_ashrrev_i32_e32 v34, 6, v0
	v_add_u32_e32 v42, s0, v34
	s_mov_b32 s0, 0x8000
	v_cmp_gt_i32_e32 vcc, s0, v42
	s_and_saveexec_b64 s[10:11], vcc
	s_mov_b32 s18, 0x80000
	s_mov_b32 s19, 0
	s_cbranch_execz .LBB0_56
	v_readlane_b32 s20, v254, 46
	v_readlane_b32 s21, v254, 47
	s_load_dwordx4 s[12:15], s[20:21], 0xd0
	s_lshl_b32 s0, s44, 10
	s_ashr_i32 s1, s0, 31
	s_lshl_b64 s[0:1], s[0:1], 2
	v_lshlrev_b32_e32 v2, 5, v0
	s_waitcnt lgkmcnt(0)
	s_add_u32 s12, s12, s0
	s_addc_u32 s13, s13, s1
	s_add_u32 s0, s14, s0
	v_and_b32_e32 v30, 0x7e0, v2
	s_addc_u32 s1, s15, s1
	global_load_dwordx4 v[2:5], v30, s[12:13]
	global_load_dwordx4 v[6:9], v30, s[12:13] offset:16
	global_load_dwordx4 v[10:13], v30, s[0:1]
	global_load_dwordx4 v[14:17], v30, s[0:1] offset:16
	global_load_dwordx4 v[18:21], v30, s[12:13] offset:2048
	global_load_dwordx4 v[22:25], v30, s[12:13] offset:2064
	global_load_dwordx4 v[26:29], v30, s[0:1] offset:2048
	s_nop 0
	global_load_dwordx4 v[30:33], v30, s[0:1] offset:2064
	v_and_b32_e32 v35, 64, v172
	v_add_u32_e32 v35, 64, v35
	v_xor_b32_e32 v36, 32, v172
	v_cmp_lt_i32_e32 vcc, v36, v35
	s_load_dwordx2 s[12:13], s[20:21], 0x190
	s_load_dwordx2 s[14:15], s[20:21], 0x130
	v_cndmask_b32_e32 v36, v172, v36, vcc
	v_lshlrev_b32_e32 v58, 2, v36
	v_xor_b32_e32 v36, 16, v172
	v_cmp_lt_i32_e32 vcc, v36, v35
	s_nop 0
	s_nop 0
	v_cndmask_b32_e32 v36, v172, v36, vcc
	v_lshlrev_b32_e32 v59, 2, v36
	v_xor_b32_e32 v36, 8, v172
	v_cmp_lt_i32_e32 vcc, v36, v35
	v_ashrrev_i32_e32 v43, 31, v42
	v_add_u32_e32 v34, 0x800, v42
	v_cndmask_b32_e32 v36, v172, v36, vcc
	v_lshlrev_b32_e32 v60, 2, v36
	v_xor_b32_e32 v36, 4, v172
	v_cmp_lt_i32_e32 vcc, v36, v35
	s_mov_b64 s[20:21], 0x400
	v_and_b32_e32 v0, 63, v0
	v_cndmask_b32_e32 v36, v172, v36, vcc
	v_lshlrev_b32_e32 v61, 2, v36
	v_xor_b32_e32 v36, 2, v172
	v_cmp_lt_i32_e32 vcc, v36, v35
	v_lshlrev_b32_e32 v0, 4, v0
	v_mov_b64_e32 v[52:53], v[0:1]
	v_cndmask_b32_e32 v36, v172, v36, vcc
	v_lshlrev_b32_e32 v62, 2, v36
	v_xor_b32_e32 v36, 1, v172
	v_cmp_lt_i32_e32 vcc, v36, v35
	s_nop 1
	v_cndmask_b32_e32 v35, v172, v36, vcc
	v_lshlrev_b32_e32 v63, 2, v35
	v_lshlrev_b64 v[36:37], 11, v[42:43]
	v_ashrrev_i32_e32 v35, 31, v34
	s_waitcnt lgkmcnt(0)
	v_lshl_add_u64 v[38:39], s[14:15], 0, v[36:37]
	v_lshlrev_b64 v[34:35], 11, v[34:35]
	v_lshl_add_u64 v[44:45], v[38:39], 0, s[20:21]
	v_lshl_add_u64 v[38:39], s[12:13], 0, v[34:35]
	v_lshl_add_u64 v[46:47], v[38:39], 0, s[20:21]
	v_lshl_add_u64 v[48:49], s[12:13], 0, v[36:37]
	v_lshl_add_u64 v[50:51], s[14:15], 0, v[34:35]
	s_mov_b64 s[12:13], 0
.LBB0_55:
	v_lshl_add_u64 v[34:35], v[48:49], 0, v[52:53]
	global_load_dwordx4 v[54:57], v[34:35], off
	global_load_dwordx4 v[74:77], v[34:35], off offset:1024
	v_lshl_add_u64 v[34:35], v[46:47], 0, v[52:53]
	global_load_dwordx4 v[38:41], v[34:35], off offset:-1024
	s_nop 0
	global_load_dwordx4 v[34:37], v[34:35], off
	v_add_u32_e32 v42, 0x100, v42
	v_readlane_b32 s0, v254, 0
	s_and_b32 s0, s0, 7
	s_lshl_b32 s0, s0, 12
	s_or_b32 s0, s0, 0x7ff
	s_waitcnt vmcnt(3)
	v_lshlrev_b32_e32 v73, 16, v54
	v_and_b32_e32 v72, 0xffff0000, v54
	v_add_f32_e32 v54, 0, v73
	v_lshlrev_b32_e32 v71, 16, v55
	v_add_f32_e32 v54, v54, v72
	v_and_b32_e32 v70, 0xffff0000, v55
	v_add_f32_e32 v54, v54, v71
	v_lshlrev_b32_e32 v69, 16, v56
	v_add_f32_e32 v54, v54, v70
	v_and_b32_e32 v68, 0xffff0000, v56
	v_add_f32_e32 v54, v54, v69
	v_lshlrev_b32_e32 v67, 16, v57
	v_add_f32_e32 v54, v54, v68
	v_and_b32_e32 v66, 0xffff0000, v57
	v_add_f32_e32 v54, v54, v67
	s_waitcnt vmcnt(2)
	v_lshlrev_b32_e32 v65, 16, v74
	v_add_f32_e32 v54, v54, v66
	v_and_b32_e32 v64, 0xffff0000, v74
	v_add_f32_e32 v54, v54, v65
	v_lshlrev_b32_e32 v43, 16, v75
	v_add_f32_e32 v54, v54, v64
	v_and_b32_e32 v0, 0xffff0000, v75
	v_add_f32_e32 v54, v54, v43
	v_add_f32_e32 v74, v54, v0
	v_lshlrev_b32_e32 v55, 16, v76
	v_and_b32_e32 v54, 0xffff0000, v76
	v_add_f32_e32 v74, v74, v55
	v_lshlrev_b32_e32 v57, 16, v77
	v_add_f32_e32 v74, v74, v54
	v_and_b32_e32 v56, 0xffff0000, v77
	v_add_f32_e32 v74, v74, v57
	v_add_f32_e32 v74, v74, v56
	ds_bpermute_b32 v75, v58, v74
	s_waitcnt lgkmcnt(0)
	v_add_f32_e32 v74, v74, v75
	ds_bpermute_b32 v75, v59, v74
	s_waitcnt lgkmcnt(0)
	v_add_f32_e32 v74, v74, v75
	ds_bpermute_b32 v75, v60, v74
	s_waitcnt lgkmcnt(0)
	v_add_f32_e32 v74, v74, v75
	ds_bpermute_b32 v75, v61, v74
	s_waitcnt lgkmcnt(0)
	v_add_f32_e32 v74, v74, v75
	ds_bpermute_b32 v75, v62, v74
	s_waitcnt lgkmcnt(0)
	v_add_f32_e32 v74, v74, v75
	ds_bpermute_b32 v75, v63, v74
	s_waitcnt lgkmcnt(0)
	v_add_f32_e32 v75, v74, v75
	v_fmac_f32_e32 v72, 0xba800000, v75
	v_fmac_f32_e32 v73, 0xba800000, v75
	v_mul_f32_e32 v78, v72, v72
	v_fmac_f32_e32 v78, v73, v73
	v_fmac_f32_e32 v71, 0xba800000, v75
	v_fmac_f32_e32 v78, v71, v71
	v_fmac_f32_e32 v70, 0xba800000, v75
	v_fmac_f32_e32 v78, v70, v70
	v_fmac_f32_e32 v69, 0xba800000, v75
	v_fmac_f32_e32 v78, v69, v69
	v_fmac_f32_e32 v68, 0xba800000, v75
	v_fmac_f32_e32 v78, v68, v68
	v_fmac_f32_e32 v67, 0xba800000, v75
	v_fmac_f32_e32 v78, v67, v67
	v_fmac_f32_e32 v66, 0xba800000, v75
	v_fmac_f32_e32 v78, v66, v66
	v_fmac_f32_e32 v65, 0xba800000, v75
	v_fmac_f32_e32 v78, v65, v65
	v_fmac_f32_e32 v64, 0xba800000, v75
	v_mul_f32_e32 v74, 0x3a800000, v75
	v_fmac_f32_e32 v78, v64, v64
	v_fmac_f32_e32 v43, 0xba800000, v75
	v_fmac_f32_e32 v78, v43, v43
	v_fmac_f32_e32 v0, 0xba800000, v75
	v_pk_add_f32 v[54:55], v[54:55], v[74:75] op_sel_hi:[1,0] neg_lo:[0,1] neg_hi:[0,1]
	v_fmac_f32_e32 v78, v0, v0
	v_pk_mul_f32 v[76:77], v[54:55], v[54:55]
	s_nop 0
	v_add_f32_e32 v75, v77, v78
	v_pk_add_f32 v[56:57], v[56:57], v[74:75] op_sel_hi:[1,0] neg_lo:[0,1] neg_hi:[0,1]
	v_add_f32_e32 v76, v76, v75
	v_pk_mul_f32 v[74:75], v[56:57], v[56:57]
	s_nop 0
	v_add_f32_e32 v75, v75, v76
	v_add_f32_e32 v74, v74, v75
	ds_bpermute_b32 v75, v58, v74
	s_waitcnt lgkmcnt(0)
; DI u32x4 pack8(const float* f) { u32x4 o; o.x = pack2(f[0], f[1]); o.y = pack2(f[2], f[3]); o.z = pack2(f[4], f[5]); o.w = pack2(f[6], f[7]); return o; }
; DI void rows_ln(PREF p, int l) {
;     ...
; #pragma unroll
;     for (int k = 0; k < 2; ++k) {
;       float v[16];
;       unpack8(raw[k][0], v); unpack8(raw[k][1], v + 8);
;       float s = 0.f;
; #pragma unroll
;       for (int i = 0; i < 16; ++i) s += v[i];
;       const float mu = wsum(s) * (1.f / 1024.f);
;       float sq = 0.f;
; #pragma unroll
;       for (int i = 0; i < 16; ++i) { v[i] -= mu; sq += v[i] * v[i]; }
;       const float rs = rsqrtf(wsum(sq) * (1.f / 1024.f) + 1e-5f);
; #pragma unroll
;       for (int h = 0; h < 2; ++h) {
;         float y[8];
; #pragma unroll
;         for (int j = 0; j < 8; ++j) y[j] = v[h * 8 + j] * rs * gg[h * 8 + j] + bb[h * 8 + j];
;         *(u32x4*)(p.X + (size_t)(row + k * (T_ / 2)) * 1024 + h * 512 + lane * 8) = pack8(y);
;       }
;     }
	v_add_f32_e32 v74, v74, v75
	ds_bpermute_b32 v75, v59, v74
	s_waitcnt lgkmcnt(0)
	v_add_f32_e32 v74, v74, v75
	ds_bpermute_b32 v75, v60, v74
	s_waitcnt lgkmcnt(0)
	v_add_f32_e32 v74, v74, v75
	ds_bpermute_b32 v75, v61, v74
	s_waitcnt lgkmcnt(0)
	v_add_f32_e32 v74, v74, v75
	ds_bpermute_b32 v75, v62, v74
	s_waitcnt lgkmcnt(0)
	v_add_f32_e32 v74, v74, v75
	ds_bpermute_b32 v75, v63, v74
	s_waitcnt lgkmcnt(0)
	v_add_f32_e32 v74, v74, v75
	v_fmamk_f32 v74, v74, 0x3a800000, v171
	v_cmp_gt_f32_e32 vcc, s61, v74
	v_mul_f32_e32 v75, 0x4b800000, v74
	s_nop 0
	v_cndmask_b32_e32 v74, v74, v75, vcc
	v_rsq_f32_e32 v74, v74
	s_nop 0
	v_mul_f32_e32 v75, 0x45800000, v74
	v_cndmask_b32_e32 v76, v74, v75, vcc
	v_mul_f32_e32 v71, v71, v76
	v_mul_f32_e32 v70, v70, v76
	v_mul_f32_e32 v69, v69, v76
	v_mul_f32_e32 v68, v68, v76
	v_mul_f32_e32 v67, v67, v76
	v_lshl_add_u64 v[74:75], v[44:45], 0, v[52:53]
	v_mul_f32_e32 v73, v73, v76
	v_mul_f32_e32 v72, v72, v76
	v_fma_f32 v71, v4, v71, v12
	v_fma_f32 v70, v5, v70, v13
	v_fma_f32 v69, v6, v69, v14
	v_fma_f32 v68, v7, v68, v15
	v_fma_f32 v77, v8, v67, v16
	v_mul_f32_e32 v66, v66, v76
	v_cvt_pk_bf16_f32 v67, v71, v70
	v_mul_f32_e32 v54, v54, v76
	v_fma_f32 v73, v2, v73, v10
	v_fma_f32 v72, v3, v72, v11
	v_fma_f32 v78, v9, v66, v17
	v_cvt_pk_bf16_f32 v66, v73, v72
	v_cvt_pk_bf16_f32 v68, v69, v68
	v_cvt_pk_bf16_f32 v69, v77, v78
	global_store_dwordx4 v[74:75], v[66:69], off offset:-1024
	v_mul_f32_e32 v65, v65, v76
	v_fma_f32 v65, v18, v65, v26
	v_fma_f32 v67, v23, v54, v31
	v_mul_f32_e32 v54, v57, v76
	v_mul_f32_e32 v64, v64, v76
	v_mul_f32_e32 v43, v43, v76
	v_mul_f32_e32 v0, v0, v76
	v_mul_f32_e32 v55, v55, v76
	v_fma_f32 v57, v24, v54, v32
	v_mul_f32_e32 v54, v56, v76
	v_fma_f32 v64, v19, v64, v27
	v_fma_f32 v43, v20, v43, v28
	v_fma_f32 v0, v21, v0, v29
	v_fma_f32 v66, v22, v55, v30
	v_fma_f32 v68, v25, v54, v33
	v_cvt_pk_bf16_f32 v54, v65, v64
	v_cvt_pk_bf16_f32 v55, v43, v0
	v_cvt_pk_bf16_f32 v56, v66, v67
	v_cvt_pk_bf16_f32 v57, v57, v68
	s_waitcnt vmcnt(2)
	v_lshlrev_b32_e32 v65, 16, v38
	global_store_dwordx4 v[74:75], v[54:57], off
	v_and_b32_e32 v64, 0xffff0000, v38
	v_lshlrev_b32_e32 v43, 16, v41
	v_lshlrev_b32_e32 v57, 16, v39
	v_and_b32_e32 v56, 0xffff0000, v39
	v_lshlrev_b32_e32 v55, 16, v40
	v_and_b32_e32 v54, 0xffff0000, v40
	s_waitcnt vmcnt(2)
	v_lshlrev_b32_e32 v40, 16, v34
	v_and_b32_e32 v39, 0xffff0000, v34
	v_add_f32_e32 v34, 0, v65
	v_add_f32_e32 v34, v34, v64
	v_add_f32_e32 v34, v34, v57
	v_add_f32_e32 v34, v34, v56
	v_add_f32_e32 v34, v34, v55
	v_add_f32_e32 v34, v34, v54
	v_and_b32_e32 v41, 0xffff0000, v41
	v_add_f32_e32 v34, v34, v43
	v_add_f32_e32 v34, v34, v41
	v_add_f32_e32 v34, v34, v40
	v_lshlrev_b32_e32 v38, 16, v35
	v_add_f32_e32 v34, v34, v39
	v_and_b32_e32 v0, 0xffff0000, v35
	v_add_f32_e32 v34, v34, v38
	v_add_f32_e32 v68, v34, v0
	v_lshlrev_b32_e32 v35, 16, v36
	v_and_b32_e32 v34, 0xffff0000, v36
	v_add_f32_e32 v36, v68, v35
	v_lshlrev_b32_e32 v67, 16, v37
	v_add_f32_e32 v36, v36, v34
	v_and_b32_e32 v66, 0xffff0000, v37
	v_add_f32_e32 v36, v36, v67
	v_add_f32_e32 v36, v36, v66
	ds_bpermute_b32 v37, v58, v36
	s_waitcnt lgkmcnt(0)
	v_add_f32_e32 v36, v36, v37
	ds_bpermute_b32 v37, v59, v36
	s_waitcnt lgkmcnt(0)
	v_add_f32_e32 v36, v36, v37
	ds_bpermute_b32 v37, v60, v36
	s_waitcnt lgkmcnt(0)
	v_add_f32_e32 v36, v36, v37
	ds_bpermute_b32 v37, v61, v36
	s_waitcnt lgkmcnt(0)
	v_add_f32_e32 v36, v36, v37
	ds_bpermute_b32 v37, v62, v36
	s_waitcnt lgkmcnt(0)
	v_add_f32_e32 v36, v36, v37
	ds_bpermute_b32 v37, v63, v36
	s_waitcnt lgkmcnt(0)
; DI u32x4 pack8(const float* f) { u32x4 o; o.x = pack2(f[0], f[1]); o.y = pack2(f[2], f[3]); o.z = pack2(f[4], f[5]); o.w = pack2(f[6], f[7]); return o; }
; DI void rows_ln(PREF p, int l) {
;     ...
; #pragma unroll
;     for (int k = 0; k < 2; ++k) {
;       float v[16];
;       unpack8(raw[k][0], v); unpack8(raw[k][1], v + 8);
;       float s = 0.f;
; #pragma unroll
;       for (int i = 0; i < 16; ++i) s += v[i];
;       const float mu = wsum(s) * (1.f / 1024.f);
;       float sq = 0.f;
; #pragma unroll
;       for (int i = 0; i < 16; ++i) { v[i] -= mu; sq += v[i] * v[i]; }
;       const float rs = rsqrtf(wsum(sq) * (1.f / 1024.f) + 1e-5f);
; #pragma unroll
;       for (int h = 0; h < 2; ++h) {
;         float y[8];
; #pragma unroll
;         for (int j = 0; j < 8; ++j) y[j] = v[h * 8 + j] * rs * gg[h * 8 + j] + bb[h * 8 + j];
;         *(u32x4*)(p.X + (size_t)(row + k * (T_ / 2)) * 1024 + h * 512 + lane * 8) = pack8(y);
;       }
;     }
;   }
	v_add_f32_e32 v37, v36, v37
	v_fmac_f32_e32 v64, 0xba800000, v37
	v_fmac_f32_e32 v65, 0xba800000, v37
	v_mul_f32_e32 v70, v64, v64
	v_fmac_f32_e32 v70, v65, v65
	v_fmac_f32_e32 v57, 0xba800000, v37
	v_fmac_f32_e32 v70, v57, v57
	v_fmac_f32_e32 v56, 0xba800000, v37
	v_fmac_f32_e32 v70, v56, v56
	v_fmac_f32_e32 v55, 0xba800000, v37
	v_fmac_f32_e32 v70, v55, v55
	v_fmac_f32_e32 v54, 0xba800000, v37
	v_fmac_f32_e32 v70, v54, v54
	v_fmac_f32_e32 v43, 0xba800000, v37
	v_fmac_f32_e32 v70, v43, v43
	v_fmac_f32_e32 v41, 0xba800000, v37
	v_fmac_f32_e32 v70, v41, v41
	v_fmac_f32_e32 v40, 0xba800000, v37
	v_fmac_f32_e32 v70, v40, v40
	v_fmac_f32_e32 v39, 0xba800000, v37
	v_mul_f32_e32 v36, 0x3a800000, v37
	v_fmac_f32_e32 v70, v39, v39
	v_fmac_f32_e32 v38, 0xba800000, v37
	v_fmac_f32_e32 v70, v38, v38
	v_fmac_f32_e32 v0, 0xba800000, v37
	v_pk_add_f32 v[34:35], v[34:35], v[36:37] op_sel_hi:[1,0] neg_lo:[0,1] neg_hi:[0,1]
	v_fmac_f32_e32 v70, v0, v0
	v_pk_mul_f32 v[68:69], v[34:35], v[34:35]
	s_nop 0
	v_add_f32_e32 v37, v69, v70
	v_add_f32_e32 v68, v68, v37
	v_pk_add_f32 v[36:37], v[66:67], v[36:37] op_sel_hi:[1,0] neg_lo:[0,1] neg_hi:[0,1]
	s_nop 0
	v_pk_mul_f32 v[66:67], v[36:37], v[36:37]
	s_nop 0
	v_add_f32_e32 v67, v67, v68
	v_add_f32_e32 v66, v66, v67
	ds_bpermute_b32 v67, v58, v66
	v_lshl_add_u64 v[68:69], v[50:51], 0, v[52:53]
	v_lshl_add_u64 v[52:53], v[52:53], 0, s[18:19]
	s_waitcnt lgkmcnt(0)
	v_add_f32_e32 v66, v66, v67
	ds_bpermute_b32 v67, v59, v66
	s_waitcnt lgkmcnt(0)
	v_add_f32_e32 v66, v66, v67
	ds_bpermute_b32 v67, v60, v66
	s_waitcnt lgkmcnt(0)
	v_add_f32_e32 v66, v66, v67
	ds_bpermute_b32 v67, v61, v66
	s_waitcnt lgkmcnt(0)
	v_add_f32_e32 v66, v66, v67
	ds_bpermute_b32 v67, v62, v66
	s_waitcnt lgkmcnt(0)
	v_add_f32_e32 v66, v66, v67
	ds_bpermute_b32 v67, v63, v66
	s_waitcnt lgkmcnt(0)
	v_add_f32_e32 v66, v66, v67
	v_fmamk_f32 v66, v66, 0x3a800000, v171
	v_cmp_gt_f32_e32 vcc, s61, v66
	v_mul_f32_e32 v67, 0x4b800000, v66
	s_nop 0
	v_cndmask_b32_e32 v66, v66, v67, vcc
	v_rsq_f32_e32 v66, v66
	s_nop 0
	v_mul_f32_e32 v67, 0x45800000, v66
	v_cndmask_b32_e32 v66, v66, v67, vcc
	v_mul_f32_e32 v57, v57, v66
	v_mul_f32_e32 v43, v43, v66
	v_fma_f32 v57, v4, v57, v12
	v_mul_f32_e32 v56, v56, v66
	v_mul_f32_e32 v55, v55, v66
	v_fma_f32 v43, v8, v43, v16
	v_mul_f32_e32 v41, v41, v66
	v_mul_f32_e32 v34, v34, v66
	v_mul_f32_e32 v65, v65, v66
	v_mul_f32_e32 v64, v64, v66
	v_fma_f32 v56, v5, v56, v13
	v_fma_f32 v67, v6, v55, v14
	v_mul_f32_e32 v54, v54, v66
	v_fma_f32 v41, v9, v41, v17
	v_cvt_pk_bf16_f32 v55, v57, v56
	v_cvt_pk_bf16_f32 v57, v43, v41
	v_fma_f32 v43, v23, v34, v31
	v_mul_f32_e32 v34, v37, v66
	v_cmp_lt_i32_e32 vcc, s0, v42
	v_fma_f32 v65, v2, v65, v10
	v_fma_f32 v64, v3, v64, v11
	v_fma_f32 v70, v7, v54, v15
	v_cvt_pk_bf16_f32 v54, v65, v64
	v_mul_f32_e32 v40, v40, v66
	v_mul_f32_e32 v39, v39, v66
	v_mul_f32_e32 v38, v38, v66
	v_mul_f32_e32 v0, v0, v66
	v_mul_f32_e32 v35, v35, v66
	v_fma_f32 v37, v24, v34, v32
	v_mul_f32_e32 v34, v36, v66
	s_or_b64 s[12:13], vcc, s[12:13]
	v_cvt_pk_bf16_f32 v56, v67, v70
	global_store_dwordx4 v[68:69], v[54:57], off
	v_fma_f32 v40, v18, v40, v26
	v_fma_f32 v39, v19, v39, v27
	v_fma_f32 v38, v20, v38, v28
	v_fma_f32 v0, v21, v0, v29
	v_fma_f32 v41, v22, v35, v30
	v_fma_f32 v54, v25, v34, v33
	v_cvt_pk_bf16_f32 v34, v40, v39
	v_cvt_pk_bf16_f32 v35, v38, v0
	v_cvt_pk_bf16_f32 v36, v41, v43
	v_cvt_pk_bf16_f32 v37, v37, v54
	global_store_dwordx4 v[68:69], v[34:37], off offset:1024
	s_andn2_b64 exec, exec, s[12:13]
	s_cbranch_execnz .LBB0_55

; DI int tidx() { int t = threadIdx.x & 255; asm volatile("" : "+v"(t)); return t; }
; DI int vbid() { return (int)blockIdx.x * 2 + half_(); }
; DI int vgrid() { return (int)gridDim.x * 2; }
; DI u32x4 pack8(const float* f) { u32x4 o; o.x = pack2(f[0], f[1]); o.y = pack2(f[2], f[3]); o.z = pack2(f[4], f[5]); o.w = pack2(f[6], f[7]); return o; }
; DI void rows_ple(PREF p, int l) {
;   const int tid = tidx(), lane = tid & 63, w = tid >> 6;
;   for (int row = vbid() * 4 + w; row < T_; row += vgrid() * 4) {
;     const u16* src = (const u16*)p.fbuf + (size_t)row * 1024;
;     float v[16];
;     unpack8(*(const u32x4*)(src + lane * 8), v);
;     unpack8(*(const u32x4*)(src + 512 + lane * 8), v + 8);
;     float xv[16];
;     unpack8(*(const u32x4*)(p.X + (size_t)row * 1024 + lane * 8), xv);
;     unpack8(*(const u32x4*)(p.X + (size_t)row * 1024 + 512 + lane * 8), xv + 8);
;     float sq = 0.f;
; #pragma unroll
;     for (int i = 0; i < 16; ++i) sq += v[i] * v[i];
;     const float rs = rsqrtf(wsum(sq) * (1.f / 1024.f) + 1e-6f);
; #pragma unroll
;     for (int h = 0; h < 2; ++h) {
;       const int c = h * 512 + lane * 8;
;       const float4 g0 = *(const float4*)(p.ple_ng + l * 1024 + c), g1 = *(const float4*)(p.ple_ng + l * 1024 + c + 4);
;       float y[8];
;       y[0] = xv[h * 8 + 0] + v[h * 8 + 0] * rs * g0.x; y[1] = xv[h * 8 + 1] + v[h * 8 + 1] * rs * g0.y;
;       y[2] = xv[h * 8 + 2] + v[h * 8 + 2] * rs * g0.z; y[3] = xv[h * 8 + 3] + v[h * 8 + 3] * rs * g0.w;
;       y[4] = xv[h * 8 + 4] + v[h * 8 + 4] * rs * g1.x; y[5] = xv[h * 8 + 5] + v[h * 8 + 5] * rs * g1.y;
;       y[6] = xv[h * 8 + 6] + v[h * 8 + 6] * rs * g1.z; y[7] = xv[h * 8 + 7] + v[h * 8 + 7] * rs * g1.w;
;       if (l == NL - 1) {
;         float4* od = (float4*)(p.out + (size_t)row * 1024 + c);
;         od[0] = make_float4(y[0], y[1], y[2], y[3]); od[1] = make_float4(y[4], y[5], y[6], y[7]);
;       } else {
;         *(u32x4*)(p.X + (size_t)row * 1024 + c) = pack8(y);
;       }
;     }
;   }
.LBB0_429:
	v_readlane_b32 s0, v254, 51
	v_readlane_b32 s1, v254, 52
	s_and_b64 vcc, exec, s[0:1]
	s_cbranch_vccz .LBB0_442
	v_readfirstlane_b32 s0, v168
	s_lshr_b32 s0, s0, 6
	v_mov_b32_e32 v2, v169
	s_and_b32 s0, s0, 0x3fffffc
	v_readlane_b32 s1, v254, 0
	s_and_b32 s31, s1, 7
	s_lshl_b32 s31, s31, 12
	s_andn2_b32 s1, s1, 7
	s_add_i32 s1, s1, s31
	s_add_i32 s0, s0, s1
	v_ashrrev_i32_e32 v0, 6, v2
	v_add_u32_e32 v14, s0, v0
	s_mov_b32 s0, 0x8000
	v_cmp_gt_i32_e32 vcc, s0, v14
	s_and_saveexec_b64 s[8:9], vcc
	s_cbranch_execz .LBB0_441
	v_and_b32_e32 v0, 64, v172
	v_add_u32_e32 v0, 64, v0
	v_xor_b32_e32 v3, 32, v172
	v_cmp_lt_i32_e32 vcc, v3, v0
	v_readlane_b32 s0, v254, 46
	v_readlane_b32 s1, v254, 47
	v_cndmask_b32_e32 v3, v172, v3, vcc
	v_lshlrev_b32_e32 v34, 2, v3
	v_xor_b32_e32 v3, 16, v172
	v_cmp_lt_i32_e32 vcc, v3, v0
	s_load_dwordx4 s[12:15], s[0:1], 0xf0
	s_lshl_b32 s0, s56, 10
	v_cndmask_b32_e32 v3, v172, v3, vcc
	v_lshlrev_b32_e32 v35, 2, v3
	v_xor_b32_e32 v3, 8, v172
	v_cmp_lt_i32_e32 vcc, v3, v0
	s_ashr_i32 s1, s0, 31
	s_lshl_b64 s[0:1], s[0:1], 2
	v_cndmask_b32_e32 v3, v172, v3, vcc
	v_lshlrev_b32_e32 v36, 2, v3
	v_xor_b32_e32 v3, 4, v172
	v_cmp_lt_i32_e32 vcc, v3, v0
	s_waitcnt lgkmcnt(0)
	s_add_u32 s0, s12, s0
	s_addc_u32 s1, s13, s1
	v_cndmask_b32_e32 v3, v172, v3, vcc
	v_lshlrev_b32_e32 v37, 2, v3
	v_xor_b32_e32 v3, 2, v172
	v_cmp_lt_i32_e32 vcc, v3, v0
	v_ashrrev_i32_e32 v15, 31, v14
	v_lshlrev_b64 v[4:5], 12, v[14:15]
	v_cndmask_b32_e32 v3, v172, v3, vcc
	v_lshlrev_b32_e32 v38, 2, v3
	v_xor_b32_e32 v3, 1, v172
	v_cmp_lt_i32_e32 vcc, v3, v0
	s_cmp_lg_u32 s56, 3
	v_lshlrev_b64 v[20:21], 11, v[14:15]
	v_cndmask_b32_e32 v0, v172, v3, vcc
	v_lshlrev_b32_e32 v39, 2, v0
	v_lshlrev_b32_e32 v0, 5, v2
	v_and_b32_e32 v0, 0x7e0, v0
	v_lshl_add_u64 v[16:17], s[0:1], 0, v[0:1]
	v_and_b32_e32 v0, 63, v2
	v_lshl_or_b32 v4, v0, 5, v4
	v_lshl_add_u64 v[2:3], s[14:15], 0, v[4:5]
	s_mov_b64 s[0:1], 0x818
	v_lshlrev_b32_e32 v0, 4, v0
	s_cselect_b64 s[10:11], -1, 0
	v_lshl_add_u64 v[18:19], v[2:3], 0, s[0:1]
	v_or3_b32 v20, v20, v0, s95
	s_mov_b64 s[12:13], 0
	s_branch .LBB0_433
.LBB0_432:
	s_mov_b32 s0, 0x100000
	s_mov_b32 s1, 0
	v_add_u32_e32 v14, 0x100, v14
	s_nop 0
	v_lshl_add_u64 v[18:19], v[18:19], 0, s[0:1]
	v_readlane_b32 s0, v254, 0
	s_and_b32 s0, s0, 7
	s_lshl_b32 s0, s0, 12
	s_or_b32 s0, s0, 0xfff
	v_cmp_lt_i32_e32 vcc, s0, v14
	s_mov_b32 s0, 0x80000
	s_mov_b32 s1, 0
	s_or_b64 s[12:13], vcc, s[12:13]
	s_nop 0
	v_lshl_add_u64 v[20:21], v[20:21], 0, s[0:1]
	s_andn2_b64 exec, exec, s[12:13]
	s_cbranch_execz .LBB0_441
